# attention: stack of fold-scale FMAs + LDS double-buffer (one barrier per unit) + wave-half barrier stagger, on top of v79
# baseline (speedup 1.0000x reference)
; #define LAS __attribute__((address_space(3)))
; __device__ __forceinline__ void attn_phase(const Params& p, LAS unsigned char* lds, int tid, int G, int bid) {
;     const int w = __builtin_amdgcn_readfirstlane(tid >> 6), lane = tid & 63, fr = lane & 15, quad = lane >> 4;
;     const unsigned char* QKV = p.ws + WS_QKV;
;     bf16_t* OG = (bf16_t*)((unsigned char*)p.out + DO_OG);
;     float* LSE = (float*)((unsigned char*)p.out + DO_LSE);
;     u32x4 kr[2], vr[2]; long nq0 = 0, nq1 = 0; int ucnt = 0;
;     u32x4 cuu[4], cgg[4], cum2 = {0u, 0u, 0u, 0u}, cum1 = cum2;
; #pragma unroll
;     for (int i = 0; i < 4; ++i) { cuu[i] = cum2; cgg[i] = cum2; }
;     for (int e = tid; e < 3 * D; e += NTHREADS) *(LAS float*)(lds + CW_OFF + e * 4) = p.conv_w[e];
;     if (bid < 3072) { const AttnUnitGeo u0 = attn_geo(bid); attn_load(QKV, u0, tid, w, fr, quad, kr, vr, nq0, nq1); }
;     for (int uid = bid; uid < 3072; uid += G) {
;         const AttnUnitGeo u = attn_geo(uid);
;     ...
; #pragma unroll
;         for (int i = 0; i < 2; ++i) { const int c = tid + NTHREADS * i, row = c >> 2, part = c & 3; *(LAS u32x4*)(lds + row * KS_PITCH + part * 16) = kr[i]; }
; #pragma unroll
;         for (int i = 0; i < 2; ++i) { const int c = tid + NTHREADS * i, part = c >> 8, row = c & 255; const u32x4 v = vr[i];
;             LAS unsigned char* vt = lds + VT_OFF + (part * 16) * VT_PITCH + row;
; #pragma unroll
;             for (int e = 0; e < 16; ++e) vt[e * VT_PITCH] = (unsigned char)((v[e >> 2] >> (8 * (e & 3))) & 0xffu); }
;         const long q0 = nq0, q1 = nq1;
;         const int qi = 16 * w + fr, tq = ((nb * 128 + qi) << dsh) + r;
;         __syncthreads();
;         if (uid + G < 3072) { const AttnUnitGeo un = attn_geo(uid + G); attn_load(QKV, un, tid, w, fr, quad, kr, vr, nq0, nq1); }
;         if (ucnt < 8) { const int it = (bid * NWAVES + w) + (ucnt >= 4 ? G * NWAVES : 0), hb = ucnt & 3, mi = (it >> 1) * 16, m0 = mi + hb * 4, ch = (it & 1) * 512 + lane * 8;
;             const bf16_t* U = (const bf16_t*)(p.ws + WS_U); const bf16_t* GZ = (const bf16_t*)(p.ws + WS_GZ);
; #pragma unroll
;             for (int i = 0; i < 4; ++i) { const size_t off = (size_t)(m0 + i) * D + ch; cuu[i] = __builtin_nontemporal_load((const u32x4*)(U + off)); cgg[i] = __builtin_nontemporal_load((const u32x4*)(GZ + off)); }
;             if (hb == 0) { cum2 = (u32x4){0u, 0u, 0u, 0u}; cum1 = cum2;
.LBB0_269:
	s_or_b64 exec, exec, s[4:5]
	s_ashr_i32 s4, s10, 6
	s_lshl_b32 s5, s4, 4
	v_and_b32_e32 v41, 15, v144
	s_add_i32 s6, s5, s8
	v_add_u32_e32 v20, s6, v41
	v_ashrrev_i32_e32 v21, 31, v20
	v_bfe_u32 v22, v144, 4, 2
	v_lshlrev_b64 v[20:21], 6, v[20:21]
	v_lshl_add_u64 v[20:21], s[0:1], 0, v[20:21]
	v_lshlrev_b32_e32 v90, 3, v22
	v_mov_b32_e32 v91, v8
	v_lshl_add_u64 v[20:21], v[20:21], 0, v[90:91]
	global_load_dwordx2 v[60:61], v[20:21], off offset:32
	global_load_dwordx2 v[62:63], v[20:21], off
	v_lshlrev_b32_e32 v20, 2, v22
	v_mbcnt_lo_u32_b32 v22, -1, 0
	v_mbcnt_hi_u32_b32 v22, -1, v22
	v_and_b32_e32 v27, 64, v22
	s_add_i32 s0, s4, s3
	v_xor_b32_e32 v23, 16, v22
	v_add_u32_e32 v27, 64, v27
	v_writelane_b32 v250, s0, 34
	s_lshl_b32 s0, s4, 9
	v_cmp_lt_i32_e32 vcc, v23, v27
	v_and_b32_e32 v24, 63, v144
	s_and_b32 s0, s0, 0x200
	v_cndmask_b32_e32 v23, v22, v23, vcc
	s_mulk_i32 s4, 0x900
	v_lshl_or_b32 v94, v24, 3, s0
	v_lshlrev_b32_e32 v122, 2, v23
	v_xor_b32_e32 v23, 32, v22
	s_add_i32 s0, s4, 0
	v_cmp_lt_i32_e32 vcc, v23, v27
	s_add_i32 s0, s0, 0x12000
	v_cmp_gt_u32_e64 s[6:7], 16, v24
	v_cndmask_b32_e32 v22, v22, v23, vcc
	v_mov_b32_e32 v23, s0
	s_movk_i32 s0, 0x110
	s_movk_i32 s1, 0x50
	v_bfe_u32 v27, v144, 2, 4
	v_writelane_b32 v250, s6, 35
	v_mul_lo_u32 v35, v86, s0
	v_mul_lo_u32 v36, v88, s0
	s_and_b32 s0, s5, 0xffffffe0
	v_or_b32_e32 v92, s5, v41
	v_lshlrev_b32_e32 v123, 2, v22
	v_mad_u32_u24 v22, v41, s1, v23
	v_or_b32_e32 v124, s5, v27
	v_mad_u32_u24 v23, v27, s1, v23
	v_writelane_b32 v250, s7, 36
	v_or_b32_e32 v27, s0, v41
	s_or_b32 s8, s5, 16
	s_add_i32 s9, s0, 32
	s_add_i32 s10, s0, 48
	s_add_i32 s11, s0, 64
	s_add_i32 s12, s0, 0x50
	s_add_i32 s13, s0, 0x60
	s_add_i32 s7, s0, 0x70
	s_add_i32 s6, s0, 0x80
	s_add_i32 s4, s0, 0x90
	v_add_u32_e32 v42, 0x80, v92
	v_mul_lo_u32 v29, v27, s1
	v_or_b32_e32 v27, s8, v41
	v_or_b32_e32 v28, s9, v41
	v_or_b32_e32 v30, s10, v41
	v_or_b32_e32 v31, s11, v41
	v_or_b32_e32 v32, s12, v41
	v_or_b32_e32 v37, s13, v41
	v_or_b32_e32 v38, s7, v41
	v_or_b32_e32 v39, s6, v41
	v_or_b32_e32 v40, s4, v41
	v_or_b32_e32 v44, s0, v20
	v_mul_lo_u32 v33, v120, s1
	v_mul_lo_u32 v34, v121, s1
	v_mul_lo_u32 v27, v27, s1
	v_mul_lo_u32 v28, v28, s1
	v_mul_lo_u32 v30, v30, s1
	v_mul_lo_u32 v31, v31, s1
	v_mul_lo_u32 v32, v32, s1
	v_mul_lo_u32 v37, v37, s1
	v_mul_lo_u32 v38, v38, s1
	v_mul_lo_u32 v39, v39, s1
	v_mul_lo_u32 v40, v40, s1
	v_sub_u32_e32 v45, v42, v44
	s_movk_i32 s1, 0x81
	v_cmp_gt_u32_e64 s[14:15], s1, v45
	s_movk_i32 s3, 0x7f
	v_cvt_f32_u32_e32 v125, v45
	v_writelane_b32 v250, s14, 37
	v_xad_u32 v45, v44, -1, v42
	s_movk_i32 s5, 0x7e
	v_writelane_b32 v250, s15, 38
	v_cmp_lt_i32_e64 s[14:15], s3, v44
	v_cvt_f32_u32_e32 v126, v45
	v_add_u32_e32 v21, 0, v90
	v_writelane_b32 v250, s14, 39
	v_sub_u32_e32 v43, v21, v20
	v_lshlrev_b32_e32 v24, 2, v94
	v_writelane_b32 v250, s15, 40
	v_cmp_gt_u32_e64 s[14:15], s1, v45
	v_or_b32_e32 v45, 2, v44
	v_sub_u32_e32 v46, v42, v45
	v_writelane_b32 v250, s14, 41
	v_cvt_f32_u32_e32 v127, v46
	v_ashrrev_i32_e32 v93, 31, v92
	v_writelane_b32 v250, s15, 42
	v_cmp_lt_i32_e64 s[14:15], s5, v44
	v_or_b32_e32 v44, 3, v44
	v_add_u32_e32 v26, 0, v84
	v_writelane_b32 v250, s14, 43
	v_add_u32_sdwa v25, v8, v144 dst_sel:DWORD dst_unused:UNUSED_PAD src0_sel:DWORD src1_sel:BYTE_0
	v_mul_u32_u24_e32 v41, 0x110, v41
	v_writelane_b32 v250, s15, 44
	v_cmp_gt_u32_e64 s[14:15], s1, v46
	v_add_u32_e32 v181, v22, v20
	v_add_u32_e32 v166, v26, v34
	v_writelane_b32 v250, s14, 45
	v_add_u32_e32 v167, v25, v35
	v_add_u32_e32 v168, v25, v36
	v_writelane_b32 v250, s15, 46
	v_cmp_lt_i32_e64 s[14:15], s3, v45
	v_sub_u32_e32 v45, v42, v44
	v_cvt_f32_u32_e32 v128, v45
	v_writelane_b32 v250, s14, 47
	v_add_u32_e32 v169, v21, v29
	v_add_u32_e32 v171, v21, v27
	v_writelane_b32 v250, s15, 48
	v_cmp_gt_u32_e64 s[14:15], s1, v45
	v_add_u32_e32 v172, v21, v28
	v_add_u32_e32 v173, v21, v30
	v_writelane_b32 v250, s14, 49
	v_add_u32_e32 v174, v21, v31
	v_add_u32_e32 v175, v21, v32
	v_writelane_b32 v250, s15, 50
	v_cmp_lt_i32_e64 s[14:15], s3, v44
	v_or_b32_e32 v44, s8, v20
	v_sub_u32_e32 v45, v42, v44
	v_writelane_b32 v250, s14, 51
	v_cvt_f32_u32_e32 v129, v45
	v_add_u32_e32 v176, v21, v37
	v_writelane_b32 v250, s15, 52
	v_cmp_gt_u32_e64 s[14:15], s1, v45
	v_xad_u32 v45, v44, -1, v42
	v_cvt_f32_u32_e32 v130, v45
	v_writelane_b32 v250, s14, 53
	v_add_u32_e32 v177, v21, v38
	v_add_u32_e32 v178, v21, v39
	v_writelane_b32 v250, s15, 54
	v_cmp_lt_i32_e64 s[14:15], s3, v44
	v_add_u32_e32 v179, v21, v40
	v_add_u32_e32 v182, v23, v84
	v_writelane_b32 v250, s14, 55
	v_mov_b64_e32 v[38:39], v[10:11]
	v_mov_b64_e32 v[30:31], v[10:11]
	v_writelane_b32 v250, s15, 56
	v_cmp_gt_u32_e64 s[14:15], s1, v45
	v_or_b32_e32 v45, 2, v44
	v_sub_u32_e32 v46, v42, v45
	v_writelane_b32 v250, s14, 57
	v_cvt_f32_u32_e32 v131, v46
	v_mov_b64_e32 v[50:51], v[10:11]
	v_writelane_b32 v250, s15, 58
	v_cmp_lt_i32_e64 s[14:15], s5, v44
	v_or_b32_e32 v44, 3, v44
	v_mov_b64_e32 v[58:59], v[10:11]
	v_writelane_b32 v250, s14, 59
	v_mov_b64_e32 v[54:55], v[10:11]
	v_mov_b32_e32 v95, v8
	v_writelane_b32 v250, s15, 60
	v_cmp_gt_u32_e64 s[14:15], s1, v46
	s_mov_b32 s80, 0x3e38aa3b
	s_mov_b32 s81, 0xc3e00000
	v_writelane_b32 v250, s14, 61
	v_mov_b32_e32 v184, 0xff800000
	v_mov_b32_e32 v185, 0x43e00000
	v_writelane_b32 v250, s15, 62
	v_cmp_lt_i32_e64 s[14:15], s3, v45
	v_sub_u32_e32 v45, v42, v44
	v_cvt_f32_u32_e32 v132, v45
	v_writelane_b32 v250, s14, 63
	v_mov_b64_e32 v[36:37], v[8:9]
	v_mov_b64_e32 v[28:29], v[8:9]
	v_writelane_b32 v249, s15, 0
	v_cmp_gt_u32_e64 s[14:15], s1, v45
	v_mov_b64_e32 v[48:49], v[8:9]
	v_mov_b64_e32 v[56:57], v[8:9]
	v_writelane_b32 v249, s14, 1
	v_mov_b64_e32 v[52:53], v[8:9]
	s_waitcnt vmcnt(0)
; #define LAS __attribute__((address_space(3)))
; __device__ __forceinline__ void attn_phase(const Params& p, LAS unsigned char* lds, int tid, int G, int bid) {
;     const int w = __builtin_amdgcn_readfirstlane(tid >> 6), lane = tid & 63, fr = lane & 15, quad = lane >> 4;
;     const unsigned char* QKV = p.ws + WS_QKV;
;     bf16_t* OG = (bf16_t*)((unsigned char*)p.out + DO_OG);
;     float* LSE = (float*)((unsigned char*)p.out + DO_LSE);
;     u32x4 kr[2], vr[2]; long nq0 = 0, nq1 = 0; int ucnt = 0;
;     u32x4 cuu[4], cgg[4], cum2 = {0u, 0u, 0u, 0u}, cum1 = cum2;
; #pragma unroll
;     for (int i = 0; i < 4; ++i) { cuu[i] = cum2; cgg[i] = cum2; }
;     for (int e = tid; e < 3 * D; e += NTHREADS) *(LAS float*)(lds + CW_OFF + e * 4) = p.conv_w[e];
;     if (bid < 3072) { const AttnUnitGeo u0 = attn_geo(bid); attn_load(QKV, u0, tid, w, fr, quad, kr, vr, nq0, nq1); }
;     for (int uid = bid; uid < 3072; uid += G) {
;         const AttnUnitGeo u = attn_geo(uid);
;     ...
; #pragma unroll
;         for (int i = 0; i < 2; ++i) { const int c = tid + NTHREADS * i, row = c >> 2, part = c & 3; *(LAS u32x4*)(lds + row * KS_PITCH + part * 16) = kr[i]; }
; #pragma unroll
;         for (int i = 0; i < 2; ++i) { const int c = tid + NTHREADS * i, part = c >> 8, row = c & 255; const u32x4 v = vr[i];
;             LAS unsigned char* vt = lds + VT_OFF + (part * 16) * VT_PITCH + row;
; #pragma unroll
;             for (int e = 0; e < 16; ++e) vt[e * VT_PITCH] = (unsigned char)((v[e >> 2] >> (8 * (e & 3))) & 0xffu); }
;         const long q0 = nq0, q1 = nq1;
;         const int qi = 16 * w + fr, tq = ((nb * 128 + qi) << dsh) + r;
;         __syncthreads();
;         if (uid + G < 3072) { const AttnUnitGeo un = attn_geo(uid + G); attn_load(QKV, un, tid, w, fr, quad, kr, vr, nq0, nq1); }
;         if (ucnt < 8) { const int it = (bid * NWAVES + w) + (ucnt >= 4 ? G * NWAVES : 0), hb = ucnt & 3, mi = (it >> 1) * 16, m0 = mi + hb * 4, ch = (it & 1) * 512 + lane * 8;
;             const bf16_t* U = (const bf16_t*)(p.ws + WS_U); const bf16_t* GZ = (const bf16_t*)(p.ws + WS_GZ);
; #pragma unroll
;             for (int i = 0; i < 4; ++i) { const size_t off = (size_t)(m0 + i) * D + ch; cuu[i] = __builtin_nontemporal_load((const u32x4*)(U + off)); cgg[i] = __builtin_nontemporal_load((const u32x4*)(GZ + off)); }
;             if (hb == 0) { cum2 = (u32x4){0u, 0u, 0u, 0u}; cum1 = cum2;
	v_mov_b64_e32 v[100:101], v[62:63]
	v_writelane_b32 v249, s15, 2
	v_cmp_lt_i32_e64 s[14:15], s3, v44
	v_or_b32_e32 v44, s9, v20
	v_sub_u32_e32 v45, v42, v44
	v_writelane_b32 v249, s14, 3
	v_cmp_gt_u32_e64 s[8:9], s1, v45
	v_cvt_f32_u32_e32 v133, v45
	v_writelane_b32 v249, s15, 4
	v_writelane_b32 v249, s8, 5
	v_xad_u32 v45, v44, -1, v42
	v_cvt_f32_u32_e32 v134, v45
	v_writelane_b32 v249, s9, 6
	v_cmp_lt_i32_e64 s[8:9], s3, v44
	v_mov_b64_e32 v[102:103], v[60:61]
	s_nop 0
	v_writelane_b32 v249, s8, 7
	s_nop 1
	v_writelane_b32 v249, s9, 8
	v_cmp_gt_u32_e64 s[8:9], s1, v45
	v_or_b32_e32 v45, 2, v44
	v_sub_u32_e32 v46, v42, v45
	v_writelane_b32 v249, s8, 9
	v_cvt_f32_u32_e32 v135, v46
	s_nop 0
	v_writelane_b32 v249, s9, 10
	v_cmp_lt_i32_e64 s[8:9], s5, v44
	v_or_b32_e32 v44, 3, v44
	s_nop 0
	v_writelane_b32 v249, s8, 11
	s_nop 1
	v_writelane_b32 v249, s9, 12
	v_cmp_gt_u32_e64 s[8:9], s1, v46
	s_nop 1
	v_writelane_b32 v249, s8, 13
	s_nop 1
	v_writelane_b32 v249, s9, 14
	v_cmp_lt_i32_e64 s[8:9], s3, v45
	v_sub_u32_e32 v45, v42, v44
	v_cvt_f32_u32_e32 v136, v45
	v_writelane_b32 v249, s8, 15
	s_nop 1
	v_writelane_b32 v249, s9, 16
	v_cmp_gt_u32_e64 s[8:9], s1, v45
	s_nop 1
	v_writelane_b32 v249, s8, 17
	s_nop 1
	v_writelane_b32 v249, s9, 18
	v_cmp_lt_i32_e64 s[8:9], s3, v44
	v_or_b32_e32 v44, s10, v20
	v_sub_u32_e32 v45, v42, v44
	v_writelane_b32 v249, s8, 19
	v_cvt_f32_u32_e32 v137, v45
	s_nop 0
	v_writelane_b32 v249, s9, 20
	v_cmp_gt_u32_e64 s[8:9], s1, v45
	v_xad_u32 v45, v44, -1, v42
	v_cvt_f32_u32_e32 v138, v45
	v_writelane_b32 v249, s8, 21
	s_nop 1
	v_writelane_b32 v249, s9, 22
	v_cmp_lt_i32_e64 s[8:9], s3, v44
	s_nop 1
	v_writelane_b32 v249, s8, 23
	s_nop 1
	v_writelane_b32 v249, s9, 24
	v_cmp_gt_u32_e64 s[8:9], s1, v45
	v_or_b32_e32 v45, 2, v44
	v_sub_u32_e32 v46, v42, v45
	v_writelane_b32 v249, s8, 25
	v_cvt_f32_u32_e32 v139, v46
	s_nop 0
	v_writelane_b32 v249, s9, 26
	v_cmp_lt_i32_e64 s[8:9], s5, v44
	v_or_b32_e32 v44, 3, v44
	s_nop 0
	v_writelane_b32 v249, s8, 27
	s_nop 1
	v_writelane_b32 v249, s9, 28
	v_cmp_gt_u32_e64 s[8:9], s1, v46
	s_nop 1
	v_writelane_b32 v249, s8, 29
	s_nop 1
	v_writelane_b32 v249, s9, 30
	v_cmp_lt_i32_e64 s[8:9], s3, v45
	v_sub_u32_e32 v45, v42, v44
	v_cvt_f32_u32_e32 v140, v45
	v_writelane_b32 v249, s8, 31
	s_nop 1
	v_writelane_b32 v249, s9, 32
	v_cmp_gt_u32_e64 s[8:9], s1, v45
	s_nop 1
	v_writelane_b32 v249, s8, 33
	s_nop 1
	v_writelane_b32 v249, s9, 34
	v_cmp_lt_i32_e64 s[8:9], s3, v44
	v_or_b32_e32 v44, s11, v20
	v_sub_u32_e32 v45, v42, v44
	v_writelane_b32 v249, s8, 35
	v_cvt_f32_u32_e32 v141, v45
	s_mov_b32 s11, s2
	s_mov_b32 s101, 0xa400
	v_writelane_b32 v249, s9, 36
	v_cmp_gt_u32_e64 s[8:9], s1, v45
	v_xad_u32 v45, v44, -1, v42
	v_cvt_f32_u32_e32 v142, v45
	v_writelane_b32 v249, s8, 37
	s_nop 1
	v_writelane_b32 v249, s9, 38
	v_cmp_lt_i32_e64 s[8:9], s3, v44
	s_nop 1
	v_writelane_b32 v249, s8, 39
	s_nop 1
	v_writelane_b32 v249, s9, 40
	v_cmp_gt_u32_e64 s[8:9], s1, v45
	v_or_b32_e32 v45, 2, v44
	v_sub_u32_e32 v46, v42, v45
	v_writelane_b32 v249, s8, 41
	v_cvt_f32_u32_e32 v143, v46
	s_nop 0
	v_writelane_b32 v249, s9, 42
	v_cmp_lt_i32_e64 s[8:9], s5, v44
	v_or_b32_e32 v44, 3, v44
	s_nop 0
	v_writelane_b32 v249, s8, 43
	s_nop 1
	v_writelane_b32 v249, s9, 44
	v_cmp_gt_u32_e64 s[8:9], s1, v46
	s_nop 1
	v_writelane_b32 v249, s8, 45
	s_nop 1
	v_writelane_b32 v249, s9, 46
	v_cmp_lt_i32_e64 s[8:9], s3, v45
	v_sub_u32_e32 v45, v42, v44
	v_cvt_f32_u32_e32 v145, v45
	v_writelane_b32 v249, s8, 47
	s_nop 1
	v_writelane_b32 v249, s9, 48
	v_cmp_gt_u32_e64 s[8:9], s1, v45
	s_nop 1
	v_writelane_b32 v249, s8, 49
	s_nop 1
	v_writelane_b32 v249, s9, 50
	v_cmp_lt_i32_e64 s[8:9], s3, v44
	v_or_b32_e32 v44, s12, v20
	v_sub_u32_e32 v45, v42, v44
	v_writelane_b32 v249, s8, 51
	v_cvt_f32_u32_e32 v146, v45
	s_nop 0
	v_writelane_b32 v249, s9, 52
	v_cmp_gt_u32_e64 s[8:9], s1, v45
	v_xad_u32 v45, v44, -1, v42
	v_cvt_f32_u32_e32 v147, v45
	v_writelane_b32 v249, s8, 53
	s_nop 1
	v_writelane_b32 v249, s9, 54
	v_cmp_lt_i32_e64 s[8:9], s3, v44
	s_nop 1
	v_writelane_b32 v249, s8, 55
	s_nop 1
	v_writelane_b32 v249, s9, 56
	v_cmp_gt_u32_e64 s[8:9], s1, v45
	v_or_b32_e32 v45, 2, v44
	v_sub_u32_e32 v46, v42, v45
	v_writelane_b32 v249, s8, 57
	v_cvt_f32_u32_e32 v148, v46
	s_nop 0
	v_writelane_b32 v249, s9, 58
	v_cmp_lt_i32_e64 s[8:9], s5, v44
	v_or_b32_e32 v44, 3, v44
	s_nop 0
	v_writelane_b32 v249, s8, 59
	s_nop 1
	v_writelane_b32 v249, s9, 60
	v_cmp_gt_u32_e64 s[8:9], s1, v46
	s_nop 1
	v_writelane_b32 v249, s8, 61
	s_nop 1
	v_writelane_b32 v249, s9, 62
	v_cmp_lt_i32_e64 s[8:9], s3, v45
	v_sub_u32_e32 v45, v42, v44
	v_cvt_f32_u32_e32 v149, v45
	v_writelane_b32 v249, s8, 63
	s_nop 1
	v_writelane_b32 v248, s9, 0
	v_cmp_gt_u32_e64 s[8:9], s1, v45
	s_nop 1
	v_writelane_b32 v248, s8, 1
	s_nop 1
	v_writelane_b32 v248, s9, 2
	v_cmp_lt_i32_e64 s[8:9], s3, v44
	v_or_b32_e32 v44, s13, v20
	v_sub_u32_e32 v45, v42, v44
	v_writelane_b32 v248, s8, 3
	v_cvt_f32_u32_e32 v150, v45
	v_cmp_lt_i32_e64 s[16:17], s5, v44
	v_writelane_b32 v248, s9, 4
	v_cmp_gt_u32_e64 s[8:9], s1, v45
	v_xad_u32 v45, v44, -1, v42
	v_cmp_gt_u32_e64 s[14:15], s1, v45
	v_writelane_b32 v248, s8, 5
	v_cvt_f32_u32_e32 v151, v45
	v_or_b32_e32 v45, 2, v44
	v_writelane_b32 v248, s9, 6
	v_cmp_lt_i32_e64 s[8:9], s3, v44
	v_or_b32_e32 v44, 3, v44
	v_sub_u32_e32 v46, v42, v45
	v_cmp_lt_i32_e64 s[20:21], s3, v45
	v_sub_u32_e32 v45, v42, v44
	v_cmp_lt_i32_e64 s[24:25], s3, v44
	v_or_b32_e32 v44, s7, v20
	v_cmp_gt_u32_e64 s[22:23], s1, v45
	v_cvt_f32_u32_e32 v153, v45
	v_sub_u32_e32 v45, v42, v44
	v_cmp_gt_u32_e64 s[26:27], s1, v45
	v_cvt_f32_u32_e32 v154, v45
	v_xad_u32 v45, v44, -1, v42
; __device__ __forceinline__ void attn_phase(const Params& p, LAS unsigned char* lds, int tid, int G, int bid) {
;     ...
;         for (int i = 0; i < 2; ++i) { const int c = tid + NTHREADS * i, row = c >> 2, part = c & 3; *(LAS u32x4*)(lds + row * KS_PITCH + part * 16) = kr[i]; }
; #pragma unroll
;         for (int i = 0; i < 2; ++i) { const int c = tid + NTHREADS * i, part = c >> 8, row = c & 255; const u32x4 v = vr[i];
;             LAS unsigned char* vt = lds + VT_OFF + (part * 16) * VT_PITCH + row;
; #pragma unroll
;             for (int e = 0; e < 16; ++e) vt[e * VT_PITCH] = (unsigned char)((v[e >> 2] >> (8 * (e & 3))) & 0xffu); }
;         const long q0 = nq0, q1 = nq1;
;         const int qi = 16 * w + fr, tq = ((nb * 128 + qi) << dsh) + r;
;         __syncthreads();
;         if (uid + G < 3072) { const AttnUnitGeo un = attn_geo(uid + G); attn_load(QKV, un, tid, w, fr, quad, kr, vr, nq0, nq1); }
;         if (ucnt < 8) { const int it = (bid * NWAVES + w) + (ucnt >= 4 ? G * NWAVES : 0), hb = ucnt & 3, mi = (it >> 1) * 16, m0 = mi + hb * 4, ch = (it & 1) * 512 + lane * 8;
;             const bf16_t* U = (const bf16_t*)(p.ws + WS_U); const bf16_t* GZ = (const bf16_t*)(p.ws + WS_GZ);
; #pragma unroll
;             for (int i = 0; i < 4; ++i) { const size_t off = (size_t)(m0 + i) * D + ch; cuu[i] = __builtin_nontemporal_load((const u32x4*)(U + off)); cgg[i] = __builtin_nontemporal_load((const u32x4*)(GZ + off)); }
;             if (hb == 0) { cum2 = (u32x4){0u, 0u, 0u, 0u}; cum1 = cum2;
;                 if ((mi & (SEQ - 1)) >= 2) { cum2 = *(const u32x4*)(U + (size_t)(mi - 2) * D + ch); cum1 = *(const u32x4*)(U + (size_t)(mi - 1) * D + ch); } } }
;         const int tstart = w & ~1;
;         f32x4 s[10];
; #pragma unroll
;         for (int tt = 0; tt < 10; ++tt) { const LAS unsigned char* kp = lds + (16 * (tstart + tt) + fr) * KS_PITCH + quad * 8;
;             const long k0 = *(const LAS long*)kp, k1 = *(const LAS long*)(kp + 32);
;             f32x4 a = {0.f, 0.f, 0.f, 0.f};
;             a = __builtin_amdgcn_mfma_f32_16x16x32_fp8_fp8(k0, q0, a, 0, 0, 0);
;             s[tt] = __builtin_amdgcn_mfma_f32_16x16x32_fp8_fp8(k1, q1, a, 0, 0, 0) * C2; }
;         const float sl2 = __builtin_amdgcn_exp2f(-8.0f * (float)(head + 1) / 12.0f) * (float)d * LOG2E;
;         float mx = -INFINITY;
; #pragma unroll
;         for (int tt = 0; tt < 10; ++tt)
; #pragma unroll
	v_cmp_lt_i32_e64 s[28:29], s3, v44
	v_cmp_gt_u32_e64 s[30:31], s1, v45
	v_cmp_lt_i32_e64 s[34:35], s5, v44
	v_cvt_f32_u32_e32 v155, v45
	v_or_b32_e32 v45, 2, v44
	v_or_b32_e32 v44, 3, v44
	v_cmp_gt_u32_e64 s[18:19], s1, v46
	v_cvt_f32_u32_e32 v152, v46
	v_sub_u32_e32 v46, v42, v45
	v_cmp_lt_i32_e64 s[38:39], s3, v45
	v_sub_u32_e32 v45, v42, v44
	v_cmp_lt_i32_e64 s[42:43], s3, v44
	v_or_b32_e32 v44, s6, v20
	v_cmp_gt_u32_e64 s[40:41], s1, v45
	v_cvt_f32_u32_e32 v157, v45
	v_sub_u32_e32 v45, v42, v44
	v_cmp_gt_u32_e64 s[44:45], s1, v45
	v_cvt_f32_u32_e32 v158, v45
	v_xad_u32 v45, v44, -1, v42
	v_cmp_lt_i32_e64 s[46:47], s3, v44
	v_cmp_gt_u32_e64 s[48:49], s1, v45
	v_cmp_lt_i32_e64 s[50:51], s5, v44
	v_cvt_f32_u32_e32 v159, v45
	v_or_b32_e32 v45, 2, v44
	v_or_b32_e32 v44, 3, v44
	v_cmp_gt_u32_e64 s[36:37], s1, v46
	v_cvt_f32_u32_e32 v156, v46
	v_sub_u32_e32 v46, v42, v45
	v_cmp_lt_i32_e64 s[54:55], s3, v45
	v_sub_u32_e32 v45, v42, v44
	v_cmp_lt_i32_e64 s[58:59], s3, v44
	v_or_b32_e32 v44, s4, v20
	v_cmp_gt_u32_e64 s[56:57], s1, v45
	v_cvt_f32_u32_e32 v161, v45
	v_sub_u32_e32 v45, v42, v44
	v_cmp_gt_u32_e64 s[60:61], s1, v45
	v_cvt_f32_u32_e32 v162, v45
	v_xad_u32 v45, v44, -1, v42
	v_cmp_lt_i32_e64 s[62:63], s3, v44
	v_cmp_gt_u32_e64 s[64:65], s1, v45
	v_cmp_lt_i32_e64 s[66:67], s5, v44
	v_cvt_f32_u32_e32 v163, v45
	v_or_b32_e32 v45, 2, v44
	v_or_b32_e32 v44, 3, v44
	v_cmp_gt_u32_e64 s[52:53], s1, v46
	v_cvt_f32_u32_e32 v160, v46
	v_sub_u32_e32 v46, v42, v45
	v_cmp_lt_i32_e64 s[70:71], s3, v45
	v_sub_u32_e32 v42, v42, v44
	v_cmp_lt_i32_e64 s[74:75], s3, v44
	s_ashr_i32 s3, s2, 31
	v_cmp_gt_u32_e64 s[68:69], s1, v46
	v_cmp_gt_u32_e64 s[72:73], s1, v42
	v_add_u32_e32 v44, s0, v43
	s_lshl_b64 s[0:1], s[2:3], 9
	s_add_u32 s0, s94, s0
	v_cvt_f32_u32_e32 v164, v46
	v_cvt_f32_u32_e32 v165, v42
	v_lshlrev_b32_e32 v42, 1, v94
	v_mov_b32_e32 v43, v8
	s_addc_u32 s1, s95, s1
	v_lshl_add_u64 v[96:97], s[90:91], 0, v[42:43]
	v_lshl_add_u64 v[42:43], v[92:93], 2, s[0:1]
	s_mov_b64 s[0:1], 0x4000000
	v_add_u32_e32 v20, 0, v24
	v_writelane_b32 v248, s8, 7
	v_lshl_add_u64 v[98:99], v[42:43], 0, s[0:1]
	s_ashr_i32 s1, s98, 31
	s_mov_b32 s0, s98
	v_add_u32_e32 v93, v26, v33
	v_add_u32_e32 v180, v44, v41
	v_add_u32_e32 v183, 0x16800, v20
	v_mov_b64_e32 v[46:47], v[10:11]
	v_mov_b64_e32 v[22:23], v[10:11]
	v_mov_b64_e32 v[42:43], v[10:11]
	v_mov_b64_e32 v[34:35], v[10:11]
	v_mov_b64_e32 v[26:27], v[10:11]
	v_writelane_b32 v248, s9, 8
	s_lshl_b64 s[88:89], s[0:1], 9
	s_mov_b32 s3, 0x41400000
	s_mov_b32 s8, 0
	v_mov_b64_e32 v[44:45], v[8:9]
	v_mov_b64_e32 v[20:21], v[8:9]
	v_mov_b64_e32 v[40:41], v[8:9]
	v_mov_b64_e32 v[32:33], v[8:9]
	v_mov_b64_e32 v[24:25], v[8:9]
	v_mov_b32_e32 v213, 0x7f800000
	v_cmp_lt_f32_e32 vcc, 0x43000000, v125
	v_cndmask_b32_e32 v125, v125, v213, vcc
	v_cmp_lt_f32_e32 vcc, 0x43000000, v126
	v_cndmask_b32_e32 v126, v126, v213, vcc
	v_cmp_lt_f32_e32 vcc, 0x43000000, v127
	v_cndmask_b32_e32 v127, v127, v213, vcc
	v_cmp_lt_f32_e32 vcc, 0x43000000, v128
	v_cndmask_b32_e32 v128, v128, v213, vcc
	v_cmp_lt_f32_e32 vcc, 0x43000000, v129
	v_cndmask_b32_e32 v129, v129, v213, vcc
	v_cmp_lt_f32_e32 vcc, 0x43000000, v130
	v_cndmask_b32_e32 v130, v130, v213, vcc
	v_cmp_lt_f32_e32 vcc, 0x43000000, v131
	v_cndmask_b32_e32 v131, v131, v213, vcc
	v_cmp_lt_f32_e32 vcc, 0x43000000, v132
	v_cndmask_b32_e32 v132, v132, v213, vcc
	v_cmp_lt_f32_e32 vcc, 0x43000000, v133
	v_cndmask_b32_e32 v133, v133, v213, vcc
	v_cmp_lt_f32_e32 vcc, 0x43000000, v134
	v_cndmask_b32_e32 v134, v134, v213, vcc
	v_cmp_lt_f32_e32 vcc, 0x43000000, v135
	v_cndmask_b32_e32 v135, v135, v213, vcc
	v_cmp_lt_f32_e32 vcc, 0x43000000, v136
	v_cndmask_b32_e32 v136, v136, v213, vcc
	v_cmp_lt_f32_e32 vcc, 0x43000000, v137
	v_cndmask_b32_e32 v137, v137, v213, vcc
	v_cmp_lt_f32_e32 vcc, 0x43000000, v138
	v_cndmask_b32_e32 v138, v138, v213, vcc
	v_cmp_lt_f32_e32 vcc, 0x43000000, v139
	v_cndmask_b32_e32 v139, v139, v213, vcc
	v_cmp_lt_f32_e32 vcc, 0x43000000, v140
	v_cndmask_b32_e32 v140, v140, v213, vcc
	v_cmp_lt_f32_e32 vcc, 0x43000000, v141
	v_cndmask_b32_e32 v141, v141, v213, vcc
	v_cmp_lt_f32_e32 vcc, 0x43000000, v142
	v_cndmask_b32_e32 v142, v142, v213, vcc
	v_cmp_lt_f32_e32 vcc, 0x43000000, v143
	v_cndmask_b32_e32 v143, v143, v213, vcc
	v_cmp_lt_f32_e32 vcc, 0x43000000, v145
	v_cndmask_b32_e32 v145, v145, v213, vcc
	v_cmp_lt_f32_e32 vcc, 0x43000000, v146
	v_cndmask_b32_e32 v146, v146, v213, vcc
	v_cmp_lt_f32_e32 vcc, 0x43000000, v147
	v_cndmask_b32_e32 v147, v147, v213, vcc
	v_cmp_lt_f32_e32 vcc, 0x43000000, v148
	v_cndmask_b32_e32 v148, v148, v213, vcc
	v_cmp_lt_f32_e32 vcc, 0x43000000, v149
	v_cndmask_b32_e32 v149, v149, v213, vcc
	v_cmp_lt_f32_e32 vcc, 0x43000000, v150
	v_cndmask_b32_e32 v150, v150, v213, vcc
	v_cmp_lt_f32_e32 vcc, 0x43000000, v151
	v_cndmask_b32_e32 v151, v151, v213, vcc
	v_cmp_lt_f32_e32 vcc, 0x43000000, v152
	v_cndmask_b32_e32 v152, v152, v213, vcc
	v_cmp_lt_f32_e32 vcc, 0x43000000, v153
	v_cndmask_b32_e32 v153, v153, v213, vcc
	v_cmp_lt_f32_e32 vcc, 0x43000000, v154
	v_cndmask_b32_e32 v154, v154, v213, vcc
	v_cmp_lt_f32_e32 vcc, 0x43000000, v155
	v_cndmask_b32_e32 v155, v155, v213, vcc
	v_cmp_lt_f32_e32 vcc, 0x43000000, v156
	v_cndmask_b32_e32 v156, v156, v213, vcc
	v_cmp_lt_f32_e32 vcc, 0x43000000, v157
	v_cndmask_b32_e32 v157, v157, v213, vcc
	v_cmp_lt_f32_e32 vcc, 0x43000000, v158
	v_cndmask_b32_e32 v158, v158, v213, vcc
	v_cmp_lt_f32_e32 vcc, 0x43000000, v159
	v_cndmask_b32_e32 v159, v159, v213, vcc
	v_cmp_lt_f32_e32 vcc, 0x43000000, v160
	v_cndmask_b32_e32 v160, v160, v213, vcc
	v_cmp_lt_f32_e32 vcc, 0x43000000, v161
	v_cndmask_b32_e32 v161, v161, v213, vcc
	v_cmp_lt_f32_e32 vcc, 0x43000000, v162
	v_cndmask_b32_e32 v162, v162, v213, vcc
	v_cmp_lt_f32_e32 vcc, 0x43000000, v163
	v_cndmask_b32_e32 v163, v163, v213, vcc
	v_cmp_lt_f32_e32 vcc, 0x43000000, v164
	v_cndmask_b32_e32 v164, v164, v213, vcc
	v_cmp_lt_f32_e32 vcc, 0x43000000, v165
	v_cndmask_b32_e32 v165, v165, v213, vcc
	v_and_b32_e32 v244, 63, v170
	v_bfe_u32 v245, v244, 1, 3
	v_and_b32_e32 v243, 1, v244
	v_lshrrev_b32_e32 v244, 4, v244
	v_and_b32_e32 v242, 3, v245
	v_lshrrev_b32_e32 v245, 2, v245
	v_lshl_add_u32 v242, v244, 2, v242
	v_lshl_add_u32 v242, v245, 4, v242
	v_lshrrev_b32_e32 v244, 2, v170
	v_and_b32_e32 v244, 0x60, v244
	v_add_u32_e32 v242, v242, v244
	v_mul_u32_u24_e32 v242, 0x50, v242
	v_lshl_add_u32 v246, v243, 3, v242
	v_add_u32_e32 v246, 0x5000, v246
	v_and_b32_e32 v244, 0xff, v170
	v_mul_u32_u24_e32 v244, 0x50, v244
	v_lshrrev_b32_e32 v245, 8, v170
	v_lshl_add_u32 v247, v245, 4, v244
	s_mov_b32 s9, 0
	s_branch .LBB0_271
; #define LAS __attribute__((address_space(3)))
; __device__ __forceinline__ void attn_phase(const Params& p, LAS unsigned char* lds, int tid, int G, int bid) {
;     ...
;     for (int uid = bid; uid < 3072; uid += G) {
;         const AttnUnitGeo u = attn_geo(uid);
;     ...
; #pragma unroll
;         for (int i = 0; i < 2; ++i) { const int c = tid + NTHREADS * i, row = c >> 2, part = c & 3; *(LAS u32x4*)(lds + row * KS_PITCH + part * 16) = kr[i]; }
; #pragma unroll
;         for (int i = 0; i < 2; ++i) { const int c = tid + NTHREADS * i, part = c >> 8, row = c & 255; const u32x4 v = vr[i];
;             LAS unsigned char* vt = lds + VT_OFF + (part * 16) * VT_PITCH + row;
; #pragma unroll
;             for (int e = 0; e < 16; ++e) vt[e * VT_PITCH] = (unsigned char)((v[e >> 2] >> (8 * (e & 3))) & 0xffu); }
;         const long q0 = nq0, q1 = nq1;
;         const int qi = 16 * w + fr, tq = ((nb * 128 + qi) << dsh) + r;
;         __syncthreads();
;         if (uid + G < 3072) { const AttnUnitGeo un = attn_geo(uid + G); attn_load(QKV, un, tid, w, fr, quad, kr, vr, nq0, nq1); }
;     ...
;         ++ucnt;
;         __syncthreads();
.LBB0_270:
	s_add_i32 s9, s9, 1
	s_add_i32 s8, s8, 4
	v_lshl_add_u64 v[98:99], v[98:99], 0, s[88:89]
	s_andn2_b64 vcc, exec, s[82:83]
	s_mov_b32 s11, s10
	s_waitcnt vmcnt(2)
	v_mov_b64_e32 v[62:63], v[100:101]
	s_waitcnt vmcnt(1)
	v_mov_b64_e32 v[60:61], v[102:103]
	s_lshl_b32 s0, s101, 1
	v_add_u32_e32 v93, s101, v93
	v_add_u32_e32 v166, s101, v166
	v_add_u32_e32 v169, s101, v169
	v_add_u32_e32 v171, s101, v171
	v_add_u32_e32 v172, s101, v172
	v_add_u32_e32 v173, s101, v173
	v_add_u32_e32 v174, s101, v174
	v_add_u32_e32 v175, s101, v175
	v_add_u32_e32 v176, s101, v176
	v_add_u32_e32 v177, s101, v177
	v_add_u32_e32 v178, s101, v178
	v_add_u32_e32 v179, s101, v179
	v_add_u32_e32 v247, s0, v247
	v_add_u32_e32 v246, s0, v246
	s_sub_i32 s101, 0, s101
	s_cbranch_vccz .LBB0_288
.LBB0_271:
	ds_write_b128 v93, v[4:7]
	ds_write_b128 v166, v[0:3]
	ds_write_b128 v247, v[16:19] offset:20480
	ds_write_b128 v247, v[12:15] offset:20512
	s_add_i32 s10, s11, s98
	s_cmpk_gt_i32 s10, 0xbff
	s_cselect_b64 s[82:83], -1, 0
	s_and_b64 vcc, exec, s[82:83]
	s_waitcnt lgkmcnt(0)
	v_readfirstlane_b32 s100, v170
	s_bitcmp1_b32 s100, 8
	s_cbranch_scc0 .Lattn_sk_top
	s_barrier
.Lattn_sk_top:
	s_cbranch_vccnz .LBB0_279
	s_mul_hi_i32 s0, s10, 0x2aaaaaab
	s_lshr_b32 s1, s0, 31
	s_ashr_i32 s0, s0, 5
	s_add_i32 s0, s0, s1
	s_mul_i32 s1, s0, 0xffffff40
	s_add_i32 s1, s10, s1
	s_ashr_i32 s1, s1, 6
	s_bfe_u32 s4, s10, 0x20004
	s_mul_i32 s0, s0, 12
	s_lshl_b32 s6, s1, 1
	s_lshl_b32 s1, s1, 2
	s_or_b32 s0, s0, s4
	s_add_i32 s0, s0, s1
	s_and_b32 s5, s10, 15
	s_ashr_i32 s1, s0, 31
	s_lshr_b32 s7, s5, s6
	s_lshl_b64 s[0:1], s[0:1], 17
	v_readlane_b32 s12, v250, 18
	v_readlane_b32 s13, v250, 19
	s_add_u32 s0, s12, s0
	s_addc_u32 s1, s13, s1
	s_sub_i32 s4, 11, s6
	s_lshl_b32 s4, s5, s4
	s_and_b32 s84, s4, 0x7fe
	s_lshl_b32 s4, s7, 7
	s_add_i32 s84, s84, s4
	s_add_i32 s85, s84, 0xffffff80
	v_lshl_add_u64 v[0:1], s[0:1], 0, v[84:85]
	s_mov_b64 s[4:5], 0x1800000
	s_cmp_lg_u32 s7, 0
	v_readlane_b32 s6, v250, 26
	v_mov_b32_e32 v2, v8
	v_mov_b32_e32 v3, v8
	v_lshl_add_u64 v[10:11], v[0:1], 0, s[4:5]
	s_cselect_b64 s[4:5], -1, 0
	v_readlane_b32 s7, v250, 27
	v_mov_b32_e32 v0, 0
	v_mov_b32_e32 v1, v8
	v_mov_b64_e32 v[6:7], v[2:3]
	s_or_b64 vcc, s[6:7], s[4:5]
	v_mov_b64_e32 v[4:5], v[0:1]
	s_and_saveexec_b64 s[6:7], vcc
	s_cbranch_execz .LBB0_274
	v_add_u32_e32 v4, s85, v120
	v_ashrrev_i32_e32 v5, 31, v4
	v_lshlrev_b64 v[4:5], 6, v[4:5]
	v_lshl_add_u64 v[4:5], v[10:11], 0, v[4:5]
	global_load_dwordx4 v[4:7], v[4:5], off

; #define LAS __attribute__((address_space(3)))
; __device__ __forceinline__ void attn_phase(const Params& p, LAS unsigned char* lds, int tid, int G, int bid) {
;     ...
;         __syncthreads();
;         if (uid + G < 3072) { const AttnUnitGeo un = attn_geo(uid + G); attn_load(QKV, un, tid, w, fr, quad, kr, vr, nq0, nq1); }
;         if (ucnt < 8) { const int it = (bid * NWAVES + w) + (ucnt >= 4 ? G * NWAVES : 0), hb = ucnt & 3, mi = (it >> 1) * 16, m0 = mi + hb * 4, ch = (it & 1) * 512 + lane * 8;
;             const bf16_t* U = (const bf16_t*)(p.ws + WS_U); const bf16_t* GZ = (const bf16_t*)(p.ws + WS_GZ);
; #pragma unroll
;             for (int i = 0; i < 4; ++i) { const size_t off = (size_t)(m0 + i) * D + ch; cuu[i] = __builtin_nontemporal_load((const u32x4*)(U + off)); cgg[i] = __builtin_nontemporal_load((const u32x4*)(GZ + off)); }
;             if (hb == 0) { cum2 = (u32x4){0u, 0u, 0u, 0u}; cum1 = cum2;
;                 if ((mi & (SEQ - 1)) >= 2) { cum2 = *(const u32x4*)(U + (size_t)(mi - 2) * D + ch); cum1 = *(const u32x4*)(U + (size_t)(mi - 1) * D + ch); } } }
;         const int tstart = w & ~1;
;         f32x4 s[10];
; #pragma unroll
;         for (int tt = 0; tt < 10; ++tt) { const LAS unsigned char* kp = lds + (16 * (tstart + tt) + fr) * KS_PITCH + quad * 8;
.LBB0_284:
	v_readfirstlane_b32 s100, v170
	s_bitcmp1_b32 s100, 8
	s_cbranch_scc1 .Lattn_sk_x
	s_barrier
